# waiting workgroups prefetch the next phase's first 32 KB of code into L2 during the grid-barrier wait (wave-wide loads of the instruction stream)
# speedup vs baseline: 1.0100x; 1.0100x over previous
.LBB0_122:
	s_or_b64 exec, exec, s[10:11]
	v_cvt_f32_u32_e32 v4, v2
	s_waitcnt vmcnt(0)
	v_readfirstlane_b32 s2, v3
	v_sub_u32_e32 v3, 0, v2
	v_rcp_iflag_f32_e32 v4, v4
	v_add_u32_e32 v5, s2, v1
	v_mul_f32_e32 v4, 0x4f7ffffe, v4
	v_cvt_u32_f32_e32 v4, v4
	v_mul_lo_u32 v1, v3, v4
	v_mul_hi_u32 v1, v4, v1
	v_add_u32_e32 v1, v4, v1
	v_mul_hi_u32 v1, v5, v1
	v_mul_lo_u32 v3, v1, v2
	v_sub_u32_e32 v3, v5, v3
	v_add_u32_e32 v4, 1, v1
	v_cmp_ge_u32_e32 vcc, v3, v2
	s_nop 1
	v_cndmask_b32_e32 v1, v1, v4, vcc
	v_sub_u32_e32 v4, v3, v2
	v_cndmask_b32_e32 v3, v3, v4, vcc
	v_add_u32_e32 v4, 1, v1
	v_cmp_ge_u32_e32 vcc, v3, v2
	v_add_u32_e32 v3, 1, v5
	s_nop 0
	v_cndmask_b32_e32 v1, v1, v4, vcc
	v_mul_lo_u32 v4, v2, v1
	v_add_u32_e32 v2, v4, v2
	s_waitcnt lgkmcnt(0)
	v_add_u32_e32 v4, 1, v1
	v_mul_lo_u32 v4, v4, v0
	v_readlane_b32 s14, v252, 2
	v_readlane_b32 s15, v252, 3
	s_add_u32 s14, s14, 0x2400
	s_addc_u32 s15, s15, 0
	v_mov_b32_e32 v6, 0
	v_cmp_ne_u32_e32 vcc, v3, v2
	s_cbranch_vccnz .Lxb_pf_0
	buffer_wbl2 sc1
	s_waitcnt vmcnt(0)
	v_mov_b32_e32 v5, 1
	global_atomic_add v6, v5, s[14:15]
	global_atomic_add v6, v5, s[14:15] offset:256
	global_atomic_add v6, v5, s[14:15] offset:512
	global_atomic_add v6, v5, s[14:15] offset:768
	global_atomic_add v6, v5, s[14:15] offset:1024
	global_atomic_add v6, v5, s[14:15] offset:1280
	global_atomic_add v6, v5, s[14:15] offset:1536
	global_atomic_add v6, v5, s[14:15] offset:1792
	global_atomic_add v6, v5, s[14:15] offset:2048
	global_atomic_add v6, v5, s[14:15] offset:2304
	global_atomic_add v6, v5, s[14:15] offset:2560
	global_atomic_add v6, v5, s[14:15] offset:2816
	global_atomic_add v6, v5, s[14:15] offset:3072
	global_atomic_add v6, v5, s[14:15] offset:3328
	global_atomic_add v6, v5, s[14:15] offset:3584
	global_atomic_add v6, v5, s[14:15] offset:3840
	s_branch .Lxb_wait_0
.Lxb_pf_0:
	s_getpc_b64 s[18:19]
	s_mov_b64 s[22:23], exec
	s_mov_b64 exec, -1
	v_mbcnt_lo_u32_b32 v254, -1, 0
	v_mbcnt_hi_u32_b32 v254, -1, v254
	v_lshlrev_b32_e32 v254, 7, v254
	global_load_dword v255, v254, s[18:19]
	s_add_u32 s18, s18, 0x2000
	s_addc_u32 s19, s19, 0
	global_load_dword v255, v254, s[18:19]
	s_add_u32 s18, s18, 0x2000
	s_addc_u32 s19, s19, 0
	global_load_dword v255, v254, s[18:19]
	s_add_u32 s18, s18, 0x2000
	s_addc_u32 s19, s19, 0
	global_load_dword v255, v254, s[18:19]
	s_mov_b64 exec, s[22:23]

.Lxb_pf_12:
	s_getpc_b64 s[18:19]
	s_mov_b64 s[22:23], exec
	s_mov_b64 exec, -1
	v_mbcnt_lo_u32_b32 v254, -1, 0
	v_mbcnt_hi_u32_b32 v254, -1, v254
	v_lshlrev_b32_e32 v254, 7, v254
	global_load_dword v255, v254, s[18:19]
	s_add_u32 s18, s18, 0x2000
	s_addc_u32 s19, s19, 0
	global_load_dword v255, v254, s[18:19]
	s_mov_b64 exec, s[22:23]

.Lxb_pf_13:
.Lxb_wait_13:
	buffer_inv sc1
	v_readlane_b32 s16, v252, 5
	s_nop 3
	s_and_b32 s16, s16, 15
	s_lshl_b32 s16, s16, 8
	s_add_u32 s14, s14, s16
	s_addc_u32 s15, s15, 0
	s_mov_b32 s16, 0
